# M2: waves load only the operands their role uses (role 0 skips the a_intra fragments, role 1 skips u), tail waits re-derived per role
# speedup vs baseline: 1.0137x; 1.0137x over previous
.Lm2_tailB_r0:
	v_pk_mul_f32 v[26:27], v[26:27], v[118:119] op_sel_hi:[1,0]
	v_pk_mul_f32 v[24:25], v[24:25], v[118:119] op_sel_hi:[1,0]
	v_pk_mul_f32 v[30:31], v[38:39], v[118:119] op_sel_hi:[1,0]
	v_pk_mul_f32 v[28:29], v[36:37], v[118:119] op_sel_hi:[1,0]
	s_waitcnt lgkmcnt(3)
	v_mfma_f32_16x16x32_bf16 v[24:27], v[16:19], v[68:71], v[24:27]
	s_add_u32 s12, s12, 0x40000
	s_addc_u32 s13, s13, 0
	s_add_i32 s18, s18, 1
	s_waitcnt lgkmcnt(1)
	v_mfma_f32_16x16x32_bf16 v[16:19], v[16:19], v[64:67], v[28:31]
	s_waitcnt vmcnt(22)
	v_mov_b64_e32 v[32:33], v[52:53]
	s_cmp_eq_u32 s12, 0x800000
	v_mov_b64_e32 v[34:35], v[54:55]
	v_mfma_f32_16x16x32_bf16 v[24:27], v[20:23], v[56:59], v[24:27]
	v_mov_b64_e32 v[28:29], v[44:45]
	s_waitcnt vmcnt(22)
	v_mov_b32_e32 v56, v126
	s_waitcnt vmcnt(21)
	v_mov_b32_e32 v57, v127
	s_waitcnt lgkmcnt(0)
	v_mfma_f32_16x16x32_bf16 v[36:39], v[20:23], v[60:63], v[16:19]
	v_cvt_pk_bf16_f32 v16, v24, v25
	v_cvt_pk_bf16_f32 v17, v26, v27
	ds_write_b64 v119, v[16:17]
	v_cvt_pk_bf16_f32 v16, v36, v37
	v_cvt_pk_bf16_f32 v17, v38, v39
	ds_write_b64 v119, v[16:17] offset:4352
	s_waitcnt lgkmcnt(0)
	s_barrier
	v_mov_b64_e32 v[16:17], v[40:41]
	v_mov_b64_e32 v[20:21], v[48:49]
	s_waitcnt vmcnt(20)
	v_mov_b32_e32 v58, v128
	s_waitcnt vmcnt(19)
	v_mov_b32_e32 v59, v129
	s_waitcnt vmcnt(18)
	v_mov_b32_e32 v60, v130
	s_waitcnt vmcnt(17)
	v_mov_b32_e32 v61, v131
	s_waitcnt vmcnt(16)
	v_mov_b32_e32 v62, v132
	s_waitcnt vmcnt(15)
	v_mov_b32_e32 v63, v133
	v_mov_b64_e32 v[30:31], v[46:47]
	v_mov_b64_e32 v[18:19], v[42:43]
	v_mov_b64_e32 v[22:23], v[50:51]
	v_mov_b32_e32 v118, v101
	s_cbranch_scc1 .LBB0_171
.Lm2_topA:
	s_add_i32 s56, s18, 1
	s_min_i32 s56, s56, 31
	s_add_u32 s14, s8, s56
	s_addc_u32 s15, s9, 0
	s_nop 0
	v_mov_b64_e32 v[66:67], v[14:15]
	s_lshl_b64 s[20:21], s[14:15], 13
	s_lshl_b64 s[14:15], s[14:15], 14
	v_mov_b64_e32 v[64:65], v[12:13]
	v_lshl_add_u64 v[12:13], v[82:83], 0, s[14:15]
	v_lshl_add_u64 v[48:49], v[84:85], 0, s[14:15]
	s_lshl_b64 s[14:15], s[56:57], 2
	s_add_u32 s14, s10, s14
	v_mov_b64_e32 v[70:71], v[10:11]
	v_mov_b64_e32 v[74:75], v[6:7]
	v_mov_b64_e32 v[78:79], v[2:3]
	s_addc_u32 s15, s11, s15
	v_mov_b64_e32 v[68:69], v[8:9]
	v_mov_b64_e32 v[72:73], v[4:5]
	v_mov_b64_e32 v[76:77], v[0:1]
	global_load_dwordx4 v[0:3], v[12:13], off
	global_load_dwordx4 v[4:7], v[12:13], off offset:64
	global_load_dwordx4 v[8:11], v[12:13], off offset:128
	global_load_dwordx4 v[12:15], v[12:13], off offset:192
	global_load_dwordx4 v[40:43], v[48:49], off
	global_load_dwordx4 v[48:51], v[48:49], off offset:64
	global_load_dword v101, v145, s[14:15]
	s_cmp_lg_u64 s[2:3], 0
	s_cbranch_scc1 .Lm2_skga
	v_lshl_add_u64 v[52:53], v[86:87], 0, s[20:21]
	global_load_dwordx4 v[44:47], v[52:53], off
	global_load_dwordx4 v[52:55], v[52:53], off offset:64
.Lm2_skga:
	s_cmp_eq_u64 s[2:3], 0
	s_cbranch_scc1 .Lm2_skua
	v_mov_b32_e32 v127, s21
	v_or_b32_e32 v126, s20, v102
	v_mov_b32_e32 v129, s21
	v_or_b32_e32 v128, s20, v104
	v_lshl_add_u64 v[126:127], v[126:127], 2, s[82:83]
	v_lshl_add_u64 v[128:129], v[128:129], 2, s[82:83]
	v_mov_b32_e32 v131, s21
	v_or_b32_e32 v130, s20, v108
	global_load_dword v126, v[126:127], off
	v_lshl_add_u64 v[130:131], v[130:131], 2, s[82:83]
	global_load_dword v127, v[128:129], off
	v_mov_b32_e32 v129, s21
	v_or_b32_e32 v128, s20, v106
	v_lshl_add_u64 v[128:129], v[128:129], 2, s[82:83]
	global_load_dword v128, v[128:129], off
	v_mov_b32_e32 v133, s21
	global_load_dword v129, v[130:131], off
	v_mov_b32_e32 v131, s21
	v_or_b32_e32 v130, s20, v110
	v_or_b32_e32 v132, s20, v112
	v_lshl_add_u64 v[130:131], v[130:131], 2, s[82:83]
	v_lshl_add_u64 v[132:133], v[132:133], 2, s[82:83]
	global_load_dword v130, v[130:131], off
	v_mov_b32_e32 v135, s21
	global_load_dword v131, v[132:133], off
	v_mov_b32_e32 v133, s21
	v_or_b32_e32 v132, s20, v114
	v_or_b32_e32 v134, s20, v116
	v_lshl_add_u64 v[132:133], v[132:133], 2, s[82:83]
	v_lshl_add_u64 v[134:135], v[134:135], 2, s[82:83]
	global_load_dword v132, v[132:133], off
	global_load_dword v133, v[134:135], off
.Lm2_skua:
	v_add_u32_e32 v142, v81, v109
	ds_read_b128 v[162:165], v142
	ds_read_b128 v[166:169], v142 offset:4352
	ds_read_b128 v[172:175], v142 offset:64
	ds_read_b128 v[176:179], v142 offset:4416
	s_andn2_b64 vcc, exec, s[2:3]
	s_waitcnt lgkmcnt(2)
	v_mfma_f32_16x16x32_bf16 v[134:137], v[76:79], v[162:165], 0
	v_mfma_f32_16x16x32_bf16 v[138:141], v[76:79], v[166:169], 0
	s_nop 2
	ds_read_b128 v[162:165], v142 offset:128
	ds_read_b128 v[166:169], v142 offset:4480
	s_waitcnt lgkmcnt(2)
	v_mfma_f32_16x16x32_bf16 v[134:137], v[72:75], v[172:175], v[134:137]
	v_mfma_f32_16x16x32_bf16 v[138:141], v[72:75], v[176:179], v[138:141]
	s_nop 2
	ds_read_b128 v[172:175], v142 offset:192
	ds_read_b128 v[176:179], v142 offset:4544
	s_waitcnt lgkmcnt(2)
	v_mfma_f32_16x16x32_bf16 v[134:137], v[68:71], v[162:165], v[134:137]
	v_mfma_f32_16x16x32_bf16 v[138:141], v[68:71], v[166:169], v[138:141]
	s_waitcnt lgkmcnt(0)
	v_mfma_f32_16x16x32_bf16 v[72:75], v[64:67], v[172:175], v[134:137]
	v_mfma_f32_16x16x32_bf16 v[76:79], v[64:67], v[176:179], v[138:141]
	s_nop 7
	s_cbranch_vccnz .Lm2_179a
	s_waitcnt vmcnt(42)
	v_sub_f32_e32 v56, v56, v72
	s_waitcnt vmcnt(41)
	v_sub_f32_e32 v57, v57, v73
	v_cvt_pk_bf16_f32 v56, v56, v57
	s_waitcnt vmcnt(40)
	v_sub_f32_e32 v57, v58, v74
	s_waitcnt vmcnt(39)
	v_sub_f32_e32 v58, v59, v75
	v_cvt_pk_bf16_f32 v57, v57, v58
	ds_write_b64 v117, v[56:57] offset:8704
	s_waitcnt vmcnt(38)
	v_sub_f32_e32 v56, v60, v76
	s_waitcnt vmcnt(37)
	v_sub_f32_e32 v57, v61, v77
	v_cvt_pk_bf16_f32 v56, v56, v57
	s_waitcnt vmcnt(35)
	v_sub_f32_e32 v57, v62, v78
	s_waitcnt vmcnt(34)
	v_sub_f32_e32 v58, v63, v79
	v_cvt_pk_bf16_f32 v57, v57, v58
	ds_write_b64 v117, v[56:57] offset:11008

.Lm2_tailA_r0:
	v_pk_mul_f32 v[26:27], v[26:27], v[118:119] op_sel_hi:[1,0]
	v_pk_mul_f32 v[24:25], v[24:25], v[118:119] op_sel_hi:[1,0]
	v_pk_mul_f32 v[30:31], v[38:39], v[118:119] op_sel_hi:[1,0]
	v_pk_mul_f32 v[28:29], v[36:37], v[118:119] op_sel_hi:[1,0]
	s_waitcnt lgkmcnt(3)
	v_mfma_f32_16x16x32_bf16 v[24:27], v[16:19], v[68:71], v[24:27]
	s_add_u32 s12, s12, 0x40000
	s_addc_u32 s13, s13, 0
	s_add_i32 s18, s18, 1
	s_waitcnt lgkmcnt(1)
	v_mfma_f32_16x16x32_bf16 v[16:19], v[16:19], v[64:67], v[28:31]
	s_waitcnt vmcnt(22)
	v_mov_b64_e32 v[32:33], v[242:243]
	s_cmp_eq_u32 s12, 0x800000
	v_mov_b64_e32 v[34:35], v[244:245]
	v_mfma_f32_16x16x32_bf16 v[24:27], v[20:23], v[56:59], v[24:27]
	v_mov_b64_e32 v[28:29], v[232:233]
	s_waitcnt vmcnt(22)
	v_mov_b32_e32 v56, v180
	s_waitcnt vmcnt(21)
	v_mov_b32_e32 v57, v181
	s_waitcnt lgkmcnt(0)
	v_mfma_f32_16x16x32_bf16 v[36:39], v[20:23], v[60:63], v[16:19]
	v_cvt_pk_bf16_f32 v16, v24, v25
	v_cvt_pk_bf16_f32 v17, v26, v27
	ds_write_b64 v119, v[16:17]
	v_cvt_pk_bf16_f32 v16, v36, v37
	v_cvt_pk_bf16_f32 v17, v38, v39
	ds_write_b64 v119, v[16:17] offset:4352
	s_waitcnt lgkmcnt(0)
	s_barrier
	v_mov_b64_e32 v[16:17], v[228:229]
	v_mov_b64_e32 v[20:21], v[236:237]
	s_waitcnt vmcnt(20)
	v_mov_b32_e32 v58, v182
	s_waitcnt vmcnt(19)
	v_mov_b32_e32 v59, v183
	s_waitcnt vmcnt(18)
	v_mov_b32_e32 v60, v184
	s_waitcnt vmcnt(17)
	v_mov_b32_e32 v61, v185
	s_waitcnt vmcnt(16)
	v_mov_b32_e32 v62, v186
	s_waitcnt vmcnt(15)
	v_mov_b32_e32 v63, v187
	v_mov_b64_e32 v[30:31], v[234:235]
	v_mov_b64_e32 v[18:19], v[230:231]
	v_mov_b64_e32 v[22:23], v[238:239]
	v_mov_b32_e32 v118, v143
	s_cbranch_scc1 .LBB0_171
.Lm2_topB:
	s_add_i32 s56, s18, 1
	s_min_i32 s56, s56, 31
	s_add_u32 s14, s8, s56
	s_addc_u32 s15, s9, 0
	s_nop 0
	v_mov_b64_e32 v[66:67], v[226:227]
	s_lshl_b64 s[20:21], s[14:15], 13
	s_lshl_b64 s[14:15], s[14:15], 14
	v_mov_b64_e32 v[64:65], v[224:225]
	v_lshl_add_u64 v[224:225], v[82:83], 0, s[14:15]
	v_lshl_add_u64 v[236:237], v[84:85], 0, s[14:15]
	s_lshl_b64 s[14:15], s[56:57], 2
	s_add_u32 s14, s10, s14
	v_mov_b64_e32 v[70:71], v[222:223]
	v_mov_b64_e32 v[74:75], v[218:219]
	v_mov_b64_e32 v[78:79], v[214:215]
	s_addc_u32 s15, s11, s15
	v_mov_b64_e32 v[68:69], v[220:221]
	v_mov_b64_e32 v[72:73], v[216:217]
	v_mov_b64_e32 v[76:77], v[212:213]
	global_load_dwordx4 v[212:215], v[224:225], off
	global_load_dwordx4 v[216:219], v[224:225], off offset:64
	global_load_dwordx4 v[220:223], v[224:225], off offset:128
	global_load_dwordx4 v[224:227], v[224:225], off offset:192
	global_load_dwordx4 v[228:231], v[236:237], off
	global_load_dwordx4 v[236:239], v[236:237], off offset:64
	global_load_dword v143, v145, s[14:15]
	s_cmp_lg_u64 s[2:3], 0
	s_cbranch_scc1 .Lm2_skgb
	v_lshl_add_u64 v[242:243], v[86:87], 0, s[20:21]
	global_load_dwordx4 v[232:235], v[242:243], off
	global_load_dwordx4 v[242:245], v[242:243], off offset:64
.Lm2_skgb:
	s_cmp_eq_u64 s[2:3], 0
	s_cbranch_scc1 .Lm2_skub
	v_mov_b32_e32 v181, s21
	v_or_b32_e32 v180, s20, v102
	v_mov_b32_e32 v183, s21
	v_or_b32_e32 v182, s20, v104
	v_lshl_add_u64 v[180:181], v[180:181], 2, s[82:83]
	v_lshl_add_u64 v[182:183], v[182:183], 2, s[82:83]
	v_mov_b32_e32 v185, s21
	v_or_b32_e32 v184, s20, v108
	global_load_dword v180, v[180:181], off
	v_lshl_add_u64 v[184:185], v[184:185], 2, s[82:83]
	global_load_dword v181, v[182:183], off
	v_mov_b32_e32 v183, s21
	v_or_b32_e32 v182, s20, v106
	v_lshl_add_u64 v[182:183], v[182:183], 2, s[82:83]
	global_load_dword v182, v[182:183], off
	v_mov_b32_e32 v187, s21
	global_load_dword v183, v[184:185], off
	v_mov_b32_e32 v185, s21
	v_or_b32_e32 v184, s20, v110
	v_or_b32_e32 v186, s20, v112
	v_lshl_add_u64 v[184:185], v[184:185], 2, s[82:83]
	v_lshl_add_u64 v[186:187], v[186:187], 2, s[82:83]
	global_load_dword v184, v[184:185], off
	v_mov_b32_e32 v189, s21
	global_load_dword v185, v[186:187], off
	v_mov_b32_e32 v187, s21
	v_or_b32_e32 v186, s20, v114
	v_or_b32_e32 v188, s20, v116
	v_lshl_add_u64 v[186:187], v[186:187], 2, s[82:83]
	v_lshl_add_u64 v[188:189], v[188:189], 2, s[82:83]
	global_load_dword v186, v[186:187], off
	global_load_dword v187, v[188:189], off

.Lm2_tailA_r1:
	v_pk_mul_f32 v[26:27], v[26:27], v[118:119] op_sel_hi:[1,0]
	v_pk_mul_f32 v[24:25], v[24:25], v[118:119] op_sel_hi:[1,0]
	v_pk_mul_f32 v[30:31], v[38:39], v[118:119] op_sel_hi:[1,0]
	v_pk_mul_f32 v[28:29], v[36:37], v[118:119] op_sel_hi:[1,0]
	s_waitcnt lgkmcnt(3)
	v_mfma_f32_16x16x32_bf16 v[24:27], v[16:19], v[68:71], v[24:27]
	s_add_u32 s12, s12, 0x40000
	s_addc_u32 s13, s13, 0
	s_add_i32 s18, s18, 1
	s_waitcnt lgkmcnt(1)
	v_mfma_f32_16x16x32_bf16 v[16:19], v[16:19], v[64:67], v[28:31]
	s_waitcnt vmcnt(25)
	v_mov_b64_e32 v[32:33], v[242:243]
	s_cmp_eq_u32 s12, 0x800000
	v_mov_b64_e32 v[34:35], v[244:245]
	v_mfma_f32_16x16x32_bf16 v[24:27], v[20:23], v[56:59], v[24:27]
	v_mov_b64_e32 v[28:29], v[232:233]
	s_waitcnt vmcnt(25)
	v_mov_b32_e32 v56, v180
	s_waitcnt vmcnt(25)
	v_mov_b32_e32 v57, v181
	s_waitcnt lgkmcnt(0)
	v_mfma_f32_16x16x32_bf16 v[36:39], v[20:23], v[60:63], v[16:19]
	v_cvt_pk_bf16_f32 v16, v24, v25
	v_cvt_pk_bf16_f32 v17, v26, v27
	ds_write_b64 v119, v[16:17]
	v_cvt_pk_bf16_f32 v16, v36, v37
	v_cvt_pk_bf16_f32 v17, v38, v39
	ds_write_b64 v119, v[16:17] offset:4352
	s_waitcnt lgkmcnt(0)
	s_barrier
	v_mov_b64_e32 v[16:17], v[228:229]
	v_mov_b64_e32 v[20:21], v[236:237]
	s_waitcnt vmcnt(25)
	v_mov_b32_e32 v58, v182
	s_waitcnt vmcnt(25)
	v_mov_b32_e32 v59, v183
	s_waitcnt vmcnt(25)
	v_mov_b32_e32 v60, v184
	s_waitcnt vmcnt(25)
	v_mov_b32_e32 v61, v185
	s_waitcnt vmcnt(25)
	v_mov_b32_e32 v62, v186
	s_waitcnt vmcnt(25)
	v_mov_b32_e32 v63, v187
	v_mov_b64_e32 v[30:31], v[234:235]
	v_mov_b64_e32 v[18:19], v[230:231]
	v_mov_b64_e32 v[22:23], v[238:239]
	v_mov_b32_e32 v118, v143
	s_cbranch_scc1 .LBB0_171
	s_branch .Lm2_topB
.Lm2_tailB_r1:
	v_pk_mul_f32 v[26:27], v[26:27], v[118:119] op_sel_hi:[1,0]
	v_pk_mul_f32 v[24:25], v[24:25], v[118:119] op_sel_hi:[1,0]
	v_pk_mul_f32 v[30:31], v[38:39], v[118:119] op_sel_hi:[1,0]
	v_pk_mul_f32 v[28:29], v[36:37], v[118:119] op_sel_hi:[1,0]
	s_waitcnt lgkmcnt(3)
	v_mfma_f32_16x16x32_bf16 v[24:27], v[16:19], v[68:71], v[24:27]
	s_add_u32 s12, s12, 0x40000
	s_addc_u32 s13, s13, 0
	s_add_i32 s18, s18, 1
	s_waitcnt lgkmcnt(1)
	v_mfma_f32_16x16x32_bf16 v[16:19], v[16:19], v[64:67], v[28:31]
	s_waitcnt vmcnt(25)
	v_mov_b64_e32 v[32:33], v[52:53]
	s_cmp_eq_u32 s12, 0x800000
	v_mov_b64_e32 v[34:35], v[54:55]
	v_mfma_f32_16x16x32_bf16 v[24:27], v[20:23], v[56:59], v[24:27]
	v_mov_b64_e32 v[28:29], v[44:45]
	s_waitcnt vmcnt(25)
	v_mov_b32_e32 v56, v126
	s_waitcnt vmcnt(25)
	v_mov_b32_e32 v57, v127
	s_waitcnt lgkmcnt(0)
	v_mfma_f32_16x16x32_bf16 v[36:39], v[20:23], v[60:63], v[16:19]
	v_cvt_pk_bf16_f32 v16, v24, v25
	v_cvt_pk_bf16_f32 v17, v26, v27
	ds_write_b64 v119, v[16:17]
	v_cvt_pk_bf16_f32 v16, v36, v37
	v_cvt_pk_bf16_f32 v17, v38, v39
	ds_write_b64 v119, v[16:17] offset:4352
	s_waitcnt lgkmcnt(0)
	s_barrier
	v_mov_b64_e32 v[16:17], v[40:41]
	v_mov_b64_e32 v[20:21], v[48:49]
	s_waitcnt vmcnt(25)
	v_mov_b32_e32 v58, v128
	s_waitcnt vmcnt(25)
	v_mov_b32_e32 v59, v129
	s_waitcnt vmcnt(25)
	v_mov_b32_e32 v60, v130
	s_waitcnt vmcnt(25)
	v_mov_b32_e32 v61, v131
	s_waitcnt vmcnt(25)
	v_mov_b32_e32 v62, v132
	s_waitcnt vmcnt(25)
	v_mov_b32_e32 v63, v133
	v_mov_b64_e32 v[30:31], v[46:47]
	v_mov_b64_e32 v[18:19], v[42:43]
	v_mov_b64_e32 v[22:23], v[50:51]
	v_mov_b32_e32 v118, v101
	s_cbranch_scc1 .LBB0_171
	s_branch .Lm2_topA
